# branch-GEMM epilogue: second group of gate loads issued early (3 behind the first group, rest as registers free up); waits recounted
# speedup vs baseline: 1.0005x; 1.0005x over previous
; __device__ __forceinline__ u32x4 pack8(f32x8 v) { u32x4 w; w.x = cvtpk(v[0], v[1]); w.y = cvtpk(v[2], v[3]); w.z = cvtpk(v[4], v[5]); w.w = cvtpk(v[6], v[7]); return w; }
;     __device__ __forceinline__ void operator()(const f32x4 (&acc)[2][2][4][2], const Unit& u, int wr, int wc, int fr, int fq, const LAS float* tab) const {
;     ...
;         } else if constexpr (MODE == 2) {
; #pragma unroll
;             for (int bj = 0; bj < 2; ++bj) {
;                 u32x4 gw[8];
; #pragma unroll
;                 for (int i = 0; i < 8; ++i) gw[i] = ld16(gate + (size_t)(row0 + (i >> 2) * HALF + (i & 3) * 16) * NPG + ct + bj * HALF);
; #pragma unroll
;                 for (int i = 0; i < 8; ++i) { const int ai = i >> 2, m = i & 3; const size_t off = (size_t)(row0 + ai * HALF + m * 16) * NPG + ct + bj * HALF;
;                     const f32x8 g = unpack8(gw[i]); const f32x4 v0 = acc[ai][bj][m][0], v1 = acc[ai][bj][m][1]; f32x8 o;
; #pragma unroll
;                     for (int e = 0; e < 8; ++e) { const float sg = __builtin_amdgcn_rcpf(1.f + __builtin_amdgcn_exp2f(-1.4426950408889634f * g[e])); o[e] = (e < 4 ? v0[e & 3] : v1[e & 3]) * sg; }
;                     *(u32x4*)(O + off) = pack8(o); } }
.LBB0_1045:
	s_lshl_b32 s1, s20, 8
	v_mbcnt_lo_u32_b32 v128, -1, 0
	v_mbcnt_hi_u32_b32 v128, -1, v128
	s_add_i32 s1, s1, s50
	v_and_or_b32 v132, v128, 15, s1
	s_lshl_b32 s0, s0, 8
	v_ashrrev_i32_e32 v128, 1, v128
	s_or_b32 s0, s0, s51
	v_and_b32_e32 v128, -8, v128
	v_add_u32_e32 v128, s0, v128
	v_ashrrev_i32_e32 v129, 31, v128
	v_lshlrev_b64 v[182:183], 1, v[128:129]
	v_ashrrev_i32_e32 v133, 31, v132
	v_lshl_add_u64 v[134:135], s[8:9], 0, v[182:183]
	v_lshlrev_b64 v[210:211], 13, v[132:133]
	v_lshl_add_u64 v[180:181], v[134:135], 0, v[210:211]
	global_load_dwordx4 v[214:217], v[180:181], off
	v_or_b32_e32 v128, 16, v132
	v_ashrrev_i32_e32 v129, 31, v128
	v_lshlrev_b64 v[208:209], 13, v[128:129]
	v_lshl_add_u64 v[178:179], v[134:135], 0, v[208:209]
	global_load_dwordx4 v[152:155], v[178:179], off
	v_or_b32_e32 v128, 32, v132
	v_ashrrev_i32_e32 v129, 31, v128
	v_lshlrev_b64 v[206:207], 13, v[128:129]
	v_lshl_add_u64 v[176:177], v[134:135], 0, v[206:207]
	global_load_dwordx4 v[148:151], v[176:177], off
	v_or_b32_e32 v128, 48, v132
	v_ashrrev_i32_e32 v129, 31, v128
	v_lshlrev_b64 v[204:205], 13, v[128:129]
	v_lshl_add_u64 v[174:175], v[134:135], 0, v[204:205]
	global_load_dwordx4 v[144:147], v[174:175], off
	s_mov_b64 s[0:1], 0x100000
	v_lshl_add_u64 v[190:191], v[210:211], 0, s[0:1]
	v_lshl_add_u64 v[172:173], v[134:135], 0, v[190:191]
	global_load_dwordx4 v[140:143], v[172:173], off
	v_add_u32_e32 v128, 0x90, v132
	v_ashrrev_i32_e32 v129, 31, v128
	v_lshlrev_b64 v[188:189], 13, v[128:129]
	v_lshl_add_u64 v[170:171], v[134:135], 0, v[188:189]
	global_load_dwordx4 v[136:139], v[170:171], off
	v_add_u32_e32 v128, 0xa0, v132
	v_ashrrev_i32_e32 v129, 31, v128
	v_lshlrev_b64 v[184:185], 13, v[128:129]
	v_lshl_add_u64 v[168:169], v[134:135], 0, v[184:185]
	global_load_dwordx4 v[128:131], v[168:169], off
	v_add_u32_e32 v132, 0xb0, v132
	v_ashrrev_i32_e32 v133, 31, v132
	v_lshlrev_b64 v[186:187], 13, v[132:133]
	v_lshl_add_u64 v[166:167], v[134:135], 0, v[186:187]
	global_load_dwordx4 v[132:135], v[166:167], off
	global_load_dwordx4 v[240:243], v[180:181], off offset:256
	global_load_dwordx4 v[244:247], v[178:179], off offset:256
	global_load_dwordx4 v[248:251], v[176:177], off offset:256
	s_mov_b64 s[0:1], -1
	s_andn2_b64 vcc, exec, s[2:3]
	s_waitcnt vmcnt(3)
	v_lshlrev_b32_e32 v218, 16, v214
	v_and_b32_e32 v219, 0xffff0000, v214
	v_lshlrev_b32_e32 v220, 16, v215
	v_and_b32_e32 v221, 0xffff0000, v215
	v_mul_f32_e32 v214, 0xbfb8aa3b, v218
	v_mul_f32_e32 v215, 0xbfb8aa3b, v219
	v_exp_f32_e32 v214, v214
	v_exp_f32_e32 v215, v215
	v_lshlrev_b32_e32 v222, 16, v216
	v_and_b32_e32 v216, 0xffff0000, v216
	v_add_f32_e32 v214, 1.0, v214
	v_add_f32_e32 v215, 1.0, v215
	v_rcp_f32_e32 v214, v214
	v_rcp_f32_e32 v215, v215
	v_lshlrev_b32_e32 v223, 16, v217
	v_and_b32_e32 v217, 0xffff0000, v217
	v_pk_mul_f32 v[124:125], v[124:125], v[214:215]
	v_mul_f32_e32 v214, 0xbfb8aa3b, v220
	v_mul_f32_e32 v215, 0xbfb8aa3b, v221
	v_exp_f32_e32 v214, v214
	v_exp_f32_e32 v215, v215
	v_add_f32_e32 v214, 1.0, v214
	v_add_f32_e32 v215, 1.0, v215
	v_rcp_f32_e32 v214, v214
	v_rcp_f32_e32 v215, v215
	s_nop 0
	v_pk_mul_f32 v[126:127], v[126:127], v[214:215]
	v_mul_f32_e32 v214, 0xbfb8aa3b, v222
	v_mul_f32_e32 v215, 0xbfb8aa3b, v216
	v_exp_f32_e32 v214, v214
	v_exp_f32_e32 v215, v215
	v_add_f32_e32 v214, 1.0, v214
	v_add_f32_e32 v215, 1.0, v215
	v_rcp_f32_e32 v214, v214
	v_rcp_f32_e32 v215, v215
	s_nop 0
	v_pk_mul_f32 v[120:121], v[120:121], v[214:215]
	v_mul_f32_e32 v214, 0xbfb8aa3b, v223
	v_mul_f32_e32 v215, 0xbfb8aa3b, v217
	v_exp_f32_e32 v214, v214
	v_exp_f32_e32 v215, v215
	v_add_f32_e32 v214, 1.0, v214
	v_add_f32_e32 v215, 1.0, v215
	v_rcp_f32_e32 v214, v214
	v_rcp_f32_e32 v215, v215
	s_nop 0
	v_pk_mul_f32 v[214:215], v[122:123], v[214:215]
	v_cvt_pk_bf16_f32 v122, v124, v125
	v_cvt_pk_bf16_f32 v124, v120, v121
	v_lshl_add_u64 v[120:121], s[6:7], 0, v[210:211]
	v_cvt_pk_bf16_f32 v123, v126, v127
	v_cvt_pk_bf16_f32 v125, v214, v215
	v_lshl_add_u64 v[120:121], v[120:121], 0, v[182:183]
	global_store_dwordx4 v[120:121], v[122:125], off
	global_load_dwordx4 v[214:217], v[174:175], off offset:256
	global_load_dwordx4 v[218:221], v[172:173], off offset:256
	v_lshlrev_b32_e32 v126, 16, v154
	v_and_b32_e32 v127, 0xffff0000, v154
	v_lshlrev_b32_e32 v122, 16, v152
	v_and_b32_e32 v123, 0xffff0000, v152
	v_mul_f32_e32 v122, 0xbfb8aa3b, v122
	v_mul_f32_e32 v123, 0xbfb8aa3b, v123
	v_exp_f32_e32 v122, v122
	v_exp_f32_e32 v123, v123
	v_lshlrev_b32_e32 v124, 16, v153
	v_and_b32_e32 v125, 0xffff0000, v153
	v_add_f32_e32 v122, 1.0, v122
	v_add_f32_e32 v123, 1.0, v123
	v_rcp_f32_e32 v122, v122
	v_rcp_f32_e32 v123, v123
	v_lshlrev_b32_e32 v152, 16, v155
	v_and_b32_e32 v153, 0xffff0000, v155
	v_pk_mul_f32 v[116:117], v[116:117], v[122:123]
	v_mul_f32_e32 v122, 0xbfb8aa3b, v124
	v_mul_f32_e32 v123, 0xbfb8aa3b, v125
	v_exp_f32_e32 v122, v122
	v_exp_f32_e32 v123, v123
	v_add_f32_e32 v122, 1.0, v122
	v_add_f32_e32 v123, 1.0, v123
	v_rcp_f32_e32 v122, v122
	v_rcp_f32_e32 v123, v123
	s_nop 0
	v_pk_mul_f32 v[118:119], v[118:119], v[122:123]
	v_mul_f32_e32 v122, 0xbfb8aa3b, v126
	v_mul_f32_e32 v123, 0xbfb8aa3b, v127
	v_exp_f32_e32 v122, v122
	v_exp_f32_e32 v123, v123
	v_add_f32_e32 v122, 1.0, v122
	v_add_f32_e32 v123, 1.0, v123
	v_rcp_f32_e32 v122, v122
	v_rcp_f32_e32 v123, v123
	s_nop 0
	v_pk_mul_f32 v[112:113], v[112:113], v[122:123]
	v_mul_f32_e32 v122, 0xbfb8aa3b, v152
	v_mul_f32_e32 v123, 0xbfb8aa3b, v153
	v_exp_f32_e32 v122, v122
	v_exp_f32_e32 v123, v123
	v_add_f32_e32 v122, 1.0, v122
	v_add_f32_e32 v123, 1.0, v123
	v_rcp_f32_e32 v122, v122
	v_rcp_f32_e32 v123, v123
	s_nop 0
; __device__ __forceinline__ u32x4 pack8(f32x8 v) { u32x4 w; w.x = cvtpk(v[0], v[1]); w.y = cvtpk(v[2], v[3]); w.z = cvtpk(v[4], v[5]); w.w = cvtpk(v[6], v[7]); return w; }
;     __device__ __forceinline__ void operator()(const f32x4 (&acc)[2][2][4][2], const Unit& u, int wr, int wc, int fr, int fq, const LAS float* tab) const {
;     ...
;         } else if constexpr (MODE == 2) {
; #pragma unroll
;             for (int bj = 0; bj < 2; ++bj) {
;                 u32x4 gw[8];
; #pragma unroll
;                 for (int i = 0; i < 8; ++i) gw[i] = ld16(gate + (size_t)(row0 + (i >> 2) * HALF + (i & 3) * 16) * NPG + ct + bj * HALF);
; #pragma unroll
;                 for (int i = 0; i < 8; ++i) { const int ai = i >> 2, m = i & 3; const size_t off = (size_t)(row0 + ai * HALF + m * 16) * NPG + ct + bj * HALF;
;                     const f32x8 g = unpack8(gw[i]); const f32x4 v0 = acc[ai][bj][m][0], v1 = acc[ai][bj][m][1]; f32x8 o;
; #pragma unroll
;                     for (int e = 0; e < 8; ++e) { const float sg = __builtin_amdgcn_rcpf(1.f + __builtin_amdgcn_exp2f(-1.4426950408889634f * g[e])); o[e] = (e < 4 ? v0[e & 3] : v1[e & 3]) * sg; }
;                     *(u32x4*)(O + off) = pack8(o); } }
	v_pk_mul_f32 v[122:123], v[114:115], v[122:123]
	v_cvt_pk_bf16_f32 v114, v116, v117
	v_cvt_pk_bf16_f32 v116, v112, v113
	v_lshl_add_u64 v[112:113], s[6:7], 0, v[208:209]
	v_cvt_pk_bf16_f32 v115, v118, v119
	v_cvt_pk_bf16_f32 v117, v122, v123
	v_lshl_add_u64 v[112:113], v[112:113], 0, v[182:183]
	global_store_dwordx4 v[112:113], v[114:117], off
	global_load_dwordx4 v[208:211], v[170:171], off offset:256
	v_lshlrev_b32_e32 v118, 16, v150
	v_and_b32_e32 v119, 0xffff0000, v150
	v_lshlrev_b32_e32 v114, 16, v148
	v_and_b32_e32 v115, 0xffff0000, v148
	v_mul_f32_e32 v114, 0xbfb8aa3b, v114
	v_mul_f32_e32 v115, 0xbfb8aa3b, v115
	v_exp_f32_e32 v114, v114
	v_exp_f32_e32 v115, v115
	v_lshlrev_b32_e32 v116, 16, v149
	v_and_b32_e32 v117, 0xffff0000, v149
	v_add_f32_e32 v114, 1.0, v114
	v_add_f32_e32 v115, 1.0, v115
	v_rcp_f32_e32 v114, v114
	v_rcp_f32_e32 v115, v115
	v_lshlrev_b32_e32 v122, 16, v151
	v_and_b32_e32 v123, 0xffff0000, v151
	v_pk_mul_f32 v[108:109], v[108:109], v[114:115]
	v_mul_f32_e32 v114, 0xbfb8aa3b, v116
	v_mul_f32_e32 v115, 0xbfb8aa3b, v117
	v_exp_f32_e32 v114, v114
	v_exp_f32_e32 v115, v115
	v_cvt_pk_bf16_f32 v108, v108, v109
	v_add_f32_e32 v114, 1.0, v114
	v_add_f32_e32 v115, 1.0, v115
	v_rcp_f32_e32 v114, v114
	v_rcp_f32_e32 v115, v115
	s_nop 0
	v_pk_mul_f32 v[110:111], v[110:111], v[114:115]
	v_mul_f32_e32 v114, 0xbfb8aa3b, v118
	v_mul_f32_e32 v115, 0xbfb8aa3b, v119
	v_exp_f32_e32 v114, v114
	v_exp_f32_e32 v115, v115
	v_cvt_pk_bf16_f32 v109, v110, v111
	v_add_f32_e32 v114, 1.0, v114
	v_add_f32_e32 v115, 1.0, v115
	v_rcp_f32_e32 v114, v114
	v_rcp_f32_e32 v115, v115
	s_nop 0
	v_pk_mul_f32 v[104:105], v[104:105], v[114:115]
	v_mul_f32_e32 v114, 0xbfb8aa3b, v122
	v_mul_f32_e32 v115, 0xbfb8aa3b, v123
	v_exp_f32_e32 v114, v114
	v_exp_f32_e32 v115, v115
	v_cvt_pk_bf16_f32 v110, v104, v105
	v_lshl_add_u64 v[104:105], s[6:7], 0, v[206:207]
	v_add_f32_e32 v114, 1.0, v114
	v_add_f32_e32 v115, 1.0, v115
	v_rcp_f32_e32 v114, v114
	v_rcp_f32_e32 v115, v115
	s_nop 0
	v_pk_mul_f32 v[106:107], v[106:107], v[114:115]
	s_nop 0
	v_cvt_pk_bf16_f32 v111, v106, v107
	v_lshl_add_u64 v[106:107], v[104:105], 0, v[182:183]
	v_lshlrev_b32_e32 v104, 16, v144
	v_and_b32_e32 v105, 0xffff0000, v144
	v_mul_f32_e32 v104, 0xbfb8aa3b, v104
	v_mul_f32_e32 v105, 0xbfb8aa3b, v105
	v_exp_f32_e32 v104, v104
	v_exp_f32_e32 v105, v105
	global_store_dwordx4 v[106:107], v[108:111], off
	v_lshlrev_b32_e32 v114, 16, v147
	v_add_f32_e32 v104, 1.0, v104
	v_add_f32_e32 v105, 1.0, v105
	v_rcp_f32_e32 v104, v104
	v_rcp_f32_e32 v105, v105
	v_lshlrev_b32_e32 v108, 16, v145
	v_and_b32_e32 v109, 0xffff0000, v145
	v_lshlrev_b32_e32 v110, 16, v146
	v_pk_mul_f32 v[100:101], v[100:101], v[104:105]
	v_mul_f32_e32 v104, 0xbfb8aa3b, v108
	v_mul_f32_e32 v105, 0xbfb8aa3b, v109
	v_exp_f32_e32 v104, v104
	v_exp_f32_e32 v105, v105
	v_and_b32_e32 v111, 0xffff0000, v146
	v_and_b32_e32 v115, 0xffff0000, v147
	v_add_f32_e32 v104, 1.0, v104
	v_add_f32_e32 v105, 1.0, v105
	v_rcp_f32_e32 v104, v104
	v_rcp_f32_e32 v105, v105
	s_nop 0
	v_pk_mul_f32 v[102:103], v[102:103], v[104:105]
	v_mul_f32_e32 v104, 0xbfb8aa3b, v110
	v_mul_f32_e32 v105, 0xbfb8aa3b, v111
	v_exp_f32_e32 v104, v104
	v_exp_f32_e32 v105, v105
	v_add_f32_e32 v104, 1.0, v104
	v_add_f32_e32 v105, 1.0, v105
	v_rcp_f32_e32 v104, v104
	v_rcp_f32_e32 v105, v105
	s_nop 0
	v_pk_mul_f32 v[104:105], v[96:97], v[104:105]
	v_mul_f32_e32 v96, 0xbfb8aa3b, v114
	v_mul_f32_e32 v97, 0xbfb8aa3b, v115
	v_exp_f32_e32 v96, v96
	v_exp_f32_e32 v97, v97
	v_add_f32_e32 v96, 1.0, v96
	v_add_f32_e32 v97, 1.0, v97
	v_rcp_f32_e32 v96, v96
	v_rcp_f32_e32 v97, v97
	s_nop 0
	v_pk_mul_f32 v[108:109], v[98:99], v[96:97]
	v_cvt_pk_bf16_f32 v96, v100, v101
	v_lshl_add_u64 v[100:101], s[6:7], 0, v[204:205]
	v_cvt_pk_bf16_f32 v97, v102, v103
	v_cvt_pk_bf16_f32 v98, v104, v105
	v_cvt_pk_bf16_f32 v99, v108, v109
	v_lshl_add_u64 v[104:105], v[100:101], 0, v[182:183]
	global_store_dwordx4 v[104:105], v[96:99], off
	global_load_dwordx4 v[204:207], v[168:169], off offset:256
	v_lshlrev_b32_e32 v100, 16, v142
	v_and_b32_e32 v101, 0xffff0000, v142
	v_lshlrev_b32_e32 v96, 16, v140
	v_and_b32_e32 v97, 0xffff0000, v140
	v_mul_f32_e32 v96, 0xbfb8aa3b, v96
	v_mul_f32_e32 v97, 0xbfb8aa3b, v97
	v_exp_f32_e32 v96, v96
	v_exp_f32_e32 v97, v97
	v_lshlrev_b32_e32 v98, 16, v141
	v_and_b32_e32 v99, 0xffff0000, v141
	v_add_f32_e32 v96, 1.0, v96
	v_add_f32_e32 v97, 1.0, v97
	v_rcp_f32_e32 v96, v96
	v_rcp_f32_e32 v97, v97
	v_lshlrev_b32_e32 v102, 16, v143
	v_and_b32_e32 v103, 0xffff0000, v143
	v_pk_mul_f32 v[92:93], v[92:93], v[96:97]
	v_mul_f32_e32 v96, 0xbfb8aa3b, v98
	v_mul_f32_e32 v97, 0xbfb8aa3b, v99
	v_exp_f32_e32 v96, v96
	v_exp_f32_e32 v97, v97
	v_add_f32_e32 v96, 1.0, v96
	v_add_f32_e32 v97, 1.0, v97
	v_rcp_f32_e32 v96, v96
	v_rcp_f32_e32 v97, v97
	s_nop 0
	v_pk_mul_f32 v[94:95], v[94:95], v[96:97]
	v_mul_f32_e32 v96, 0xbfb8aa3b, v100
	v_mul_f32_e32 v97, 0xbfb8aa3b, v101
	v_exp_f32_e32 v96, v96
	v_exp_f32_e32 v97, v97
	v_add_f32_e32 v96, 1.0, v96
	v_add_f32_e32 v97, 1.0, v97
	v_rcp_f32_e32 v96, v96
	v_rcp_f32_e32 v97, v97
	s_nop 0
	v_pk_mul_f32 v[96:97], v[88:89], v[96:97]
	v_mul_f32_e32 v88, 0xbfb8aa3b, v102
	v_mul_f32_e32 v89, 0xbfb8aa3b, v103
	v_exp_f32_e32 v88, v88
	v_exp_f32_e32 v89, v89
	v_add_f32_e32 v88, 1.0, v88
	v_add_f32_e32 v89, 1.0, v89
	v_rcp_f32_e32 v88, v88
	v_rcp_f32_e32 v89, v89
	s_nop 0
	v_pk_mul_f32 v[98:99], v[90:91], v[88:89]
	v_cvt_pk_bf16_f32 v88, v92, v93
	v_lshl_add_u64 v[92:93], s[6:7], 0, v[190:191]
	v_cvt_pk_bf16_f32 v89, v94, v95
	v_cvt_pk_bf16_f32 v90, v96, v97
	v_cvt_pk_bf16_f32 v91, v98, v99
	v_lshl_add_u64 v[102:103], v[92:93], 0, v[182:183]
; __device__ __forceinline__ u32x4 pack8(f32x8 v) { u32x4 w; w.x = cvtpk(v[0], v[1]); w.y = cvtpk(v[2], v[3]); w.z = cvtpk(v[4], v[5]); w.w = cvtpk(v[6], v[7]); return w; }
;     __device__ __forceinline__ void operator()(const f32x4 (&acc)[2][2][4][2], const Unit& u, int wr, int wc, int fr, int fq, const LAS float* tab) const {
;     ...
;         } else if constexpr (MODE == 2) {
; #pragma unroll
;             for (int bj = 0; bj < 2; ++bj) {
;                 u32x4 gw[8];
; #pragma unroll
;                 for (int i = 0; i < 8; ++i) gw[i] = ld16(gate + (size_t)(row0 + (i >> 2) * HALF + (i & 3) * 16) * NPG + ct + bj * HALF);
; #pragma unroll
;                 for (int i = 0; i < 8; ++i) { const int ai = i >> 2, m = i & 3; const size_t off = (size_t)(row0 + ai * HALF + m * 16) * NPG + ct + bj * HALF;
;                     const f32x8 g = unpack8(gw[i]); const f32x4 v0 = acc[ai][bj][m][0], v1 = acc[ai][bj][m][1]; f32x8 o;
; #pragma unroll
;                     for (int e = 0; e < 8; ++e) { const float sg = __builtin_amdgcn_rcpf(1.f + __builtin_amdgcn_exp2f(-1.4426950408889634f * g[e])); o[e] = (e < 4 ? v0[e & 3] : v1[e & 3]) * sg; }
;                     *(u32x4*)(O + off) = pack8(o); } }
	global_store_dwordx4 v[102:103], v[88:91], off
	v_lshlrev_b32_e32 v92, 16, v138
	v_and_b32_e32 v93, 0xffff0000, v138
	v_lshlrev_b32_e32 v88, 16, v136
	v_and_b32_e32 v89, 0xffff0000, v136
	v_mul_f32_e32 v88, 0xbfb8aa3b, v88
	v_mul_f32_e32 v89, 0xbfb8aa3b, v89
	v_exp_f32_e32 v88, v88
	v_exp_f32_e32 v89, v89
	v_lshlrev_b32_e32 v90, 16, v137
	v_and_b32_e32 v91, 0xffff0000, v137
	v_add_f32_e32 v88, 1.0, v88
	v_add_f32_e32 v89, 1.0, v89
	v_rcp_f32_e32 v88, v88
	v_rcp_f32_e32 v89, v89
	v_lshlrev_b32_e32 v94, 16, v139
	v_and_b32_e32 v95, 0xffff0000, v139
	v_pk_mul_f32 v[84:85], v[84:85], v[88:89]
	v_mul_f32_e32 v88, 0xbfb8aa3b, v90
	v_mul_f32_e32 v89, 0xbfb8aa3b, v91
	v_exp_f32_e32 v88, v88
	v_exp_f32_e32 v89, v89
	v_add_f32_e32 v88, 1.0, v88
	v_add_f32_e32 v89, 1.0, v89
	v_rcp_f32_e32 v88, v88
	v_rcp_f32_e32 v89, v89
	s_nop 0
	v_pk_mul_f32 v[86:87], v[86:87], v[88:89]
	v_mul_f32_e32 v88, 0xbfb8aa3b, v92
	v_mul_f32_e32 v89, 0xbfb8aa3b, v93
	v_exp_f32_e32 v88, v88
	v_exp_f32_e32 v89, v89
	v_add_f32_e32 v88, 1.0, v88
	v_add_f32_e32 v89, 1.0, v89
	v_rcp_f32_e32 v88, v88
	v_rcp_f32_e32 v89, v89
	s_nop 0
	v_pk_mul_f32 v[88:89], v[80:81], v[88:89]
	v_mul_f32_e32 v80, 0xbfb8aa3b, v94
	v_mul_f32_e32 v81, 0xbfb8aa3b, v95
	v_exp_f32_e32 v80, v80
	v_exp_f32_e32 v81, v81
	v_add_f32_e32 v80, 1.0, v80
	v_add_f32_e32 v81, 1.0, v81
	v_rcp_f32_e32 v80, v80
	v_rcp_f32_e32 v81, v81
	s_nop 0
	v_pk_mul_f32 v[90:91], v[82:83], v[80:81]
	v_cvt_pk_bf16_f32 v80, v84, v85
	v_lshl_add_u64 v[84:85], s[6:7], 0, v[188:189]
	v_cvt_pk_bf16_f32 v81, v86, v87
	v_cvt_pk_bf16_f32 v82, v88, v89
	v_cvt_pk_bf16_f32 v83, v90, v91
	v_lshl_add_u64 v[100:101], v[84:85], 0, v[182:183]
	global_store_dwordx4 v[100:101], v[80:83], off
	global_load_dwordx4 v[188:191], v[166:167], off offset:256
	v_lshlrev_b32_e32 v84, 16, v130
	v_and_b32_e32 v85, 0xffff0000, v130
	v_lshlrev_b32_e32 v80, 16, v128
	v_and_b32_e32 v81, 0xffff0000, v128
	v_mul_f32_e32 v80, 0xbfb8aa3b, v80
	v_mul_f32_e32 v81, 0xbfb8aa3b, v81
	v_exp_f32_e32 v80, v80
	v_exp_f32_e32 v81, v81
	v_lshlrev_b32_e32 v82, 16, v129
	v_and_b32_e32 v83, 0xffff0000, v129
	v_add_f32_e32 v80, 1.0, v80
	v_add_f32_e32 v81, 1.0, v81
	v_rcp_f32_e32 v80, v80
	v_rcp_f32_e32 v81, v81
	v_lshlrev_b32_e32 v86, 16, v131
	v_and_b32_e32 v87, 0xffff0000, v131
	v_pk_mul_f32 v[76:77], v[76:77], v[80:81]
	v_mul_f32_e32 v80, 0xbfb8aa3b, v82
	v_mul_f32_e32 v81, 0xbfb8aa3b, v83
	v_exp_f32_e32 v80, v80
	v_exp_f32_e32 v81, v81
	v_add_f32_e32 v80, 1.0, v80
	v_add_f32_e32 v81, 1.0, v81
	v_rcp_f32_e32 v80, v80
	v_rcp_f32_e32 v81, v81
	s_nop 0
	v_pk_mul_f32 v[78:79], v[78:79], v[80:81]
	v_mul_f32_e32 v80, 0xbfb8aa3b, v84
	v_mul_f32_e32 v81, 0xbfb8aa3b, v85
	v_exp_f32_e32 v80, v80
	v_exp_f32_e32 v81, v81
	v_add_f32_e32 v80, 1.0, v80
	v_add_f32_e32 v81, 1.0, v81
	v_rcp_f32_e32 v80, v80
	v_rcp_f32_e32 v81, v81
	s_nop 0
	v_pk_mul_f32 v[80:81], v[72:73], v[80:81]
	v_mul_f32_e32 v72, 0xbfb8aa3b, v86
	v_mul_f32_e32 v73, 0xbfb8aa3b, v87
	v_exp_f32_e32 v72, v72
	v_exp_f32_e32 v73, v73
	v_add_f32_e32 v72, 1.0, v72
	v_add_f32_e32 v73, 1.0, v73
	v_rcp_f32_e32 v72, v72
	v_rcp_f32_e32 v73, v73
	s_nop 0
	v_pk_mul_f32 v[82:83], v[74:75], v[72:73]
	v_cvt_pk_bf16_f32 v72, v76, v77
	v_lshl_add_u64 v[76:77], s[6:7], 0, v[184:185]
	v_cvt_pk_bf16_f32 v73, v78, v79
	v_cvt_pk_bf16_f32 v74, v80, v81
	v_cvt_pk_bf16_f32 v75, v82, v83
	v_lshl_add_u64 v[98:99], v[76:77], 0, v[182:183]
	global_store_dwordx4 v[98:99], v[72:75], off
	v_lshlrev_b32_e32 v76, 16, v134
	v_and_b32_e32 v77, 0xffff0000, v134
	v_lshlrev_b32_e32 v72, 16, v132
	v_and_b32_e32 v73, 0xffff0000, v132
	v_mul_f32_e32 v72, 0xbfb8aa3b, v72
	v_mul_f32_e32 v73, 0xbfb8aa3b, v73
	v_exp_f32_e32 v72, v72
	v_exp_f32_e32 v73, v73
	v_lshlrev_b32_e32 v74, 16, v133
	v_and_b32_e32 v75, 0xffff0000, v133
	v_add_f32_e32 v72, 1.0, v72
	v_add_f32_e32 v73, 1.0, v73
	v_rcp_f32_e32 v72, v72
	v_rcp_f32_e32 v73, v73
	v_lshlrev_b32_e32 v78, 16, v135
	v_and_b32_e32 v79, 0xffff0000, v135
	v_pk_mul_f32 v[68:69], v[68:69], v[72:73]
	v_mul_f32_e32 v72, 0xbfb8aa3b, v74
	v_mul_f32_e32 v73, 0xbfb8aa3b, v75
	v_exp_f32_e32 v72, v72
	v_exp_f32_e32 v73, v73
	v_add_f32_e32 v72, 1.0, v72
	v_add_f32_e32 v73, 1.0, v73
	v_rcp_f32_e32 v72, v72
	v_rcp_f32_e32 v73, v73
	s_nop 0
	v_pk_mul_f32 v[70:71], v[70:71], v[72:73]
	v_mul_f32_e32 v72, 0xbfb8aa3b, v76
	v_mul_f32_e32 v73, 0xbfb8aa3b, v77
	v_exp_f32_e32 v72, v72
	v_exp_f32_e32 v73, v73
	v_add_f32_e32 v72, 1.0, v72
	v_add_f32_e32 v73, 1.0, v73
	v_rcp_f32_e32 v72, v72
	v_rcp_f32_e32 v73, v73
	s_nop 0
	v_pk_mul_f32 v[72:73], v[64:65], v[72:73]
	v_mul_f32_e32 v64, 0xbfb8aa3b, v78
	v_mul_f32_e32 v65, 0xbfb8aa3b, v79
	v_exp_f32_e32 v64, v64
	v_exp_f32_e32 v65, v65
	v_add_f32_e32 v64, 1.0, v64
	v_add_f32_e32 v65, 1.0, v65
	v_rcp_f32_e32 v64, v64
	v_rcp_f32_e32 v65, v65
	s_nop 0
	v_pk_mul_f32 v[74:75], v[66:67], v[64:65]
	v_cvt_pk_bf16_f32 v64, v68, v69
	v_lshl_add_u64 v[68:69], s[6:7], 0, v[186:187]
	v_cvt_pk_bf16_f32 v65, v70, v71
	v_cvt_pk_bf16_f32 v66, v72, v73
	v_cvt_pk_bf16_f32 v67, v74, v75
	v_lshl_add_u64 v[96:97], v[68:69], 0, v[182:183]
	global_store_dwordx4 v[96:97], v[64:67], off
	s_waitcnt vmcnt(15)
; __device__ __forceinline__ u32x4 pack8(f32x8 v) { u32x4 w; w.x = cvtpk(v[0], v[1]); w.y = cvtpk(v[2], v[3]); w.z = cvtpk(v[4], v[5]); w.w = cvtpk(v[6], v[7]); return w; }
;     __device__ __forceinline__ void operator()(const f32x4 (&acc)[2][2][4][2], const Unit& u, int wr, int wc, int fr, int fq, const LAS float* tab) const {
;     ...
; #pragma unroll
;                 for (int i = 0; i < 8; ++i) { const int ai = i >> 2, m = i & 3; const size_t off = (size_t)(row0 + ai * HALF + m * 16) * NPG + ct + bj * HALF;
;                     const f32x8 g = unpack8(gw[i]); const f32x4 v0 = acc[ai][bj][m][0], v1 = acc[ai][bj][m][1]; f32x8 o;
; #pragma unroll
;                     for (int e = 0; e < 8; ++e) { const float sg = __builtin_amdgcn_rcpf(1.f + __builtin_amdgcn_exp2f(-1.4426950408889634f * g[e])); o[e] = (e < 4 ? v0[e & 3] : v1[e & 3]) * sg; }
;                     *(u32x4*)(O + off) = pack8(o); } }
	v_lshlrev_b32_e32 v108, 16, v240
	v_and_b32_e32 v109, 0xffff0000, v240
	v_lshlrev_b32_e32 v110, 16, v241
	v_and_b32_e32 v111, 0xffff0000, v241
	v_mul_f32_e32 v88, 0xbfb8aa3b, v108
	v_mul_f32_e32 v89, 0xbfb8aa3b, v109
	v_exp_f32_e32 v88, v88
	v_exp_f32_e32 v89, v89
	v_lshlrev_b32_e32 v114, 16, v242
	v_and_b32_e32 v90, 0xffff0000, v242
	v_add_f32_e32 v88, 1.0, v88
	v_add_f32_e32 v89, 1.0, v89
	v_rcp_f32_e32 v88, v88
	v_rcp_f32_e32 v89, v89
	v_lshlrev_b32_e32 v115, 16, v243
	v_and_b32_e32 v91, 0xffff0000, v243
	v_pk_mul_f32 v[60:61], v[60:61], v[88:89]
	v_mul_f32_e32 v88, 0xbfb8aa3b, v110
	v_mul_f32_e32 v89, 0xbfb8aa3b, v111
	v_exp_f32_e32 v88, v88
	v_exp_f32_e32 v89, v89
	v_add_f32_e32 v88, 1.0, v88
	v_add_f32_e32 v89, 1.0, v89
	v_rcp_f32_e32 v88, v88
	v_rcp_f32_e32 v89, v89
	s_nop 0
	v_pk_mul_f32 v[62:63], v[62:63], v[88:89]
	v_mul_f32_e32 v88, 0xbfb8aa3b, v114
	v_mul_f32_e32 v89, 0xbfb8aa3b, v90
	v_exp_f32_e32 v88, v88
	v_exp_f32_e32 v89, v89
	v_add_f32_e32 v88, 1.0, v88
	v_add_f32_e32 v89, 1.0, v89
	v_rcp_f32_e32 v88, v88
	v_rcp_f32_e32 v89, v89
	s_nop 0
	v_pk_mul_f32 v[88:89], v[56:57], v[88:89]
	v_mul_f32_e32 v56, 0xbfb8aa3b, v115
	v_mul_f32_e32 v57, 0xbfb8aa3b, v91
	v_exp_f32_e32 v56, v56
	v_exp_f32_e32 v57, v57
	v_add_f32_e32 v56, 1.0, v56
	v_add_f32_e32 v57, 1.0, v57
	v_rcp_f32_e32 v56, v56
	v_rcp_f32_e32 v57, v57
	s_nop 0
	v_pk_mul_f32 v[90:91], v[58:59], v[56:57]
	v_cvt_pk_bf16_f32 v56, v60, v61
	v_cvt_pk_bf16_f32 v57, v62, v63
	v_cvt_pk_bf16_f32 v58, v88, v89
	v_cvt_pk_bf16_f32 v59, v90, v91
	global_store_dwordx4 v[120:121], v[56:59], off offset:256
	s_waitcnt vmcnt(15)
	v_lshlrev_b32_e32 v60, 16, v246
	v_and_b32_e32 v61, 0xffff0000, v246
	v_lshlrev_b32_e32 v56, 16, v244
	v_and_b32_e32 v57, 0xffff0000, v244
	v_mul_f32_e32 v56, 0xbfb8aa3b, v56
	v_mul_f32_e32 v57, 0xbfb8aa3b, v57
	v_exp_f32_e32 v56, v56
	v_exp_f32_e32 v57, v57
	v_lshlrev_b32_e32 v58, 16, v245
	v_and_b32_e32 v59, 0xffff0000, v245
	v_add_f32_e32 v56, 1.0, v56
	v_add_f32_e32 v57, 1.0, v57
	v_rcp_f32_e32 v56, v56
	v_rcp_f32_e32 v57, v57
	v_lshlrev_b32_e32 v62, 16, v247
	v_and_b32_e32 v63, 0xffff0000, v247
	v_pk_mul_f32 v[52:53], v[52:53], v[56:57]
	v_mul_f32_e32 v56, 0xbfb8aa3b, v58
	v_mul_f32_e32 v57, 0xbfb8aa3b, v59
	v_exp_f32_e32 v56, v56
	v_exp_f32_e32 v57, v57
	v_add_f32_e32 v56, 1.0, v56
	v_add_f32_e32 v57, 1.0, v57
	v_rcp_f32_e32 v56, v56
	v_rcp_f32_e32 v57, v57
	s_nop 0
	v_pk_mul_f32 v[54:55], v[54:55], v[56:57]
	v_mul_f32_e32 v56, 0xbfb8aa3b, v60
	v_mul_f32_e32 v57, 0xbfb8aa3b, v61
	v_exp_f32_e32 v56, v56
	v_exp_f32_e32 v57, v57
	v_add_f32_e32 v56, 1.0, v56
	v_add_f32_e32 v57, 1.0, v57
	v_rcp_f32_e32 v56, v56
	v_rcp_f32_e32 v57, v57
	s_nop 0
	v_pk_mul_f32 v[56:57], v[48:49], v[56:57]
	v_mul_f32_e32 v48, 0xbfb8aa3b, v62
	v_mul_f32_e32 v49, 0xbfb8aa3b, v63
	v_exp_f32_e32 v48, v48
	v_exp_f32_e32 v49, v49
	v_add_f32_e32 v48, 1.0, v48
	v_add_f32_e32 v49, 1.0, v49
	v_rcp_f32_e32 v48, v48
	v_rcp_f32_e32 v49, v49
	s_nop 0
	v_pk_mul_f32 v[58:59], v[50:51], v[48:49]
	v_cvt_pk_bf16_f32 v48, v52, v53
	v_cvt_pk_bf16_f32 v49, v54, v55
	v_cvt_pk_bf16_f32 v50, v56, v57
	v_cvt_pk_bf16_f32 v51, v58, v59
	global_store_dwordx4 v[112:113], v[48:51], off offset:256
	s_waitcnt vmcnt(15)
	v_lshlrev_b32_e32 v52, 16, v250
	v_and_b32_e32 v53, 0xffff0000, v250
	v_lshlrev_b32_e32 v48, 16, v248
	v_and_b32_e32 v49, 0xffff0000, v248
	v_mul_f32_e32 v48, 0xbfb8aa3b, v48
	v_mul_f32_e32 v49, 0xbfb8aa3b, v49
	v_exp_f32_e32 v48, v48
	v_exp_f32_e32 v49, v49
	v_lshlrev_b32_e32 v50, 16, v249
	v_and_b32_e32 v51, 0xffff0000, v249
	v_add_f32_e32 v48, 1.0, v48
	v_add_f32_e32 v49, 1.0, v49
	v_rcp_f32_e32 v48, v48
	v_rcp_f32_e32 v49, v49
	v_lshlrev_b32_e32 v54, 16, v251
	v_and_b32_e32 v55, 0xffff0000, v251
	v_pk_mul_f32 v[44:45], v[44:45], v[48:49]
	v_mul_f32_e32 v48, 0xbfb8aa3b, v50
	v_mul_f32_e32 v49, 0xbfb8aa3b, v51
	v_exp_f32_e32 v48, v48
	v_exp_f32_e32 v49, v49
	v_add_f32_e32 v48, 1.0, v48
	v_add_f32_e32 v49, 1.0, v49
	v_rcp_f32_e32 v48, v48
	v_rcp_f32_e32 v49, v49
	s_nop 0
	v_pk_mul_f32 v[46:47], v[46:47], v[48:49]
	v_mul_f32_e32 v48, 0xbfb8aa3b, v52
	v_mul_f32_e32 v49, 0xbfb8aa3b, v53
	v_exp_f32_e32 v48, v48
	v_exp_f32_e32 v49, v49
	v_add_f32_e32 v48, 1.0, v48
	v_add_f32_e32 v49, 1.0, v49
	v_rcp_f32_e32 v48, v48
	v_rcp_f32_e32 v49, v49
	s_nop 0
	v_pk_mul_f32 v[48:49], v[40:41], v[48:49]
	v_mul_f32_e32 v40, 0xbfb8aa3b, v54
	v_mul_f32_e32 v41, 0xbfb8aa3b, v55
	v_exp_f32_e32 v40, v40
	v_exp_f32_e32 v41, v41
	v_add_f32_e32 v40, 1.0, v40
	v_add_f32_e32 v41, 1.0, v41
	v_rcp_f32_e32 v40, v40
	v_rcp_f32_e32 v41, v41
	s_nop 0
	v_pk_mul_f32 v[50:51], v[42:43], v[40:41]
	v_cvt_pk_bf16_f32 v40, v44, v45
	v_cvt_pk_bf16_f32 v41, v46, v47
	v_cvt_pk_bf16_f32 v42, v48, v49
	v_cvt_pk_bf16_f32 v43, v50, v51
	global_store_dwordx4 v[106:107], v[40:43], off offset:256
	s_waitcnt vmcnt(14)
	v_lshlrev_b32_e32 v44, 16, v216
	v_and_b32_e32 v45, 0xffff0000, v216
	v_lshlrev_b32_e32 v40, 16, v214
	v_and_b32_e32 v41, 0xffff0000, v214
	v_mul_f32_e32 v40, 0xbfb8aa3b, v40
	v_mul_f32_e32 v41, 0xbfb8aa3b, v41
	v_exp_f32_e32 v40, v40
	v_exp_f32_e32 v41, v41
	v_lshlrev_b32_e32 v42, 16, v215
	v_and_b32_e32 v43, 0xffff0000, v215
	v_add_f32_e32 v40, 1.0, v40
	v_add_f32_e32 v41, 1.0, v41
	v_rcp_f32_e32 v40, v40
	v_rcp_f32_e32 v41, v41
	v_lshlrev_b32_e32 v46, 16, v217
	v_and_b32_e32 v47, 0xffff0000, v217
	v_pk_mul_f32 v[36:37], v[36:37], v[40:41]
	v_mul_f32_e32 v40, 0xbfb8aa3b, v42
	v_mul_f32_e32 v41, 0xbfb8aa3b, v43
	v_exp_f32_e32 v40, v40
	v_exp_f32_e32 v41, v41
	v_add_f32_e32 v40, 1.0, v40
	v_add_f32_e32 v41, 1.0, v41
	v_rcp_f32_e32 v40, v40
	v_rcp_f32_e32 v41, v41
	s_nop 0
	v_pk_mul_f32 v[38:39], v[38:39], v[40:41]
	v_mul_f32_e32 v40, 0xbfb8aa3b, v44
	v_mul_f32_e32 v41, 0xbfb8aa3b, v45
	v_exp_f32_e32 v40, v40
	v_exp_f32_e32 v41, v41
	v_add_f32_e32 v40, 1.0, v40
	v_add_f32_e32 v41, 1.0, v41
	v_rcp_f32_e32 v40, v40
	v_rcp_f32_e32 v41, v41
	s_nop 0
	v_pk_mul_f32 v[40:41], v[32:33], v[40:41]
	v_mul_f32_e32 v32, 0xbfb8aa3b, v46
	v_mul_f32_e32 v33, 0xbfb8aa3b, v47
	v_exp_f32_e32 v32, v32
	v_exp_f32_e32 v33, v33
	v_add_f32_e32 v32, 1.0, v32
	v_add_f32_e32 v33, 1.0, v33
	v_rcp_f32_e32 v32, v32
	v_rcp_f32_e32 v33, v33
	s_nop 0
	v_pk_mul_f32 v[42:43], v[34:35], v[32:33]
	v_cvt_pk_bf16_f32 v32, v36, v37
	v_cvt_pk_bf16_f32 v33, v38, v39
	v_cvt_pk_bf16_f32 v34, v40, v41
	v_cvt_pk_bf16_f32 v35, v42, v43
	global_store_dwordx4 v[104:105], v[32:35], off offset:256
	s_waitcnt vmcnt(14)
; __device__ __forceinline__ u32x4 pack8(f32x8 v) { u32x4 w; w.x = cvtpk(v[0], v[1]); w.y = cvtpk(v[2], v[3]); w.z = cvtpk(v[4], v[5]); w.w = cvtpk(v[6], v[7]); return w; }
;     __device__ __forceinline__ void operator()(const f32x4 (&acc)[2][2][4][2], const Unit& u, int wr, int wc, int fr, int fq, const LAS float* tab) const {
;     ...
; #pragma unroll
;                 for (int i = 0; i < 8; ++i) { const int ai = i >> 2, m = i & 3; const size_t off = (size_t)(row0 + ai * HALF + m * 16) * NPG + ct + bj * HALF;
;                     const f32x8 g = unpack8(gw[i]); const f32x4 v0 = acc[ai][bj][m][0], v1 = acc[ai][bj][m][1]; f32x8 o;
; #pragma unroll
;                     for (int e = 0; e < 8; ++e) { const float sg = __builtin_amdgcn_rcpf(1.f + __builtin_amdgcn_exp2f(-1.4426950408889634f * g[e])); o[e] = (e < 4 ? v0[e & 3] : v1[e & 3]) * sg; }
;                     *(u32x4*)(O + off) = pack8(o); } }
	v_lshlrev_b32_e32 v36, 16, v220
	v_and_b32_e32 v37, 0xffff0000, v220
	v_lshlrev_b32_e32 v32, 16, v218
	v_and_b32_e32 v33, 0xffff0000, v218
	v_mul_f32_e32 v32, 0xbfb8aa3b, v32
	v_mul_f32_e32 v33, 0xbfb8aa3b, v33
	v_exp_f32_e32 v32, v32
	v_exp_f32_e32 v33, v33
	v_lshlrev_b32_e32 v34, 16, v219
	v_and_b32_e32 v35, 0xffff0000, v219
	v_add_f32_e32 v32, 1.0, v32
	v_add_f32_e32 v33, 1.0, v33
	v_rcp_f32_e32 v32, v32
	v_rcp_f32_e32 v33, v33
	v_lshlrev_b32_e32 v38, 16, v221
	v_and_b32_e32 v39, 0xffff0000, v221
	v_pk_mul_f32 v[28:29], v[28:29], v[32:33]
	v_mul_f32_e32 v32, 0xbfb8aa3b, v34
	v_mul_f32_e32 v33, 0xbfb8aa3b, v35
	v_exp_f32_e32 v32, v32
	v_exp_f32_e32 v33, v33
	v_add_f32_e32 v32, 1.0, v32
	v_add_f32_e32 v33, 1.0, v33
	v_rcp_f32_e32 v32, v32
	v_rcp_f32_e32 v33, v33
	s_nop 0
	v_pk_mul_f32 v[30:31], v[30:31], v[32:33]
	v_mul_f32_e32 v32, 0xbfb8aa3b, v36
	v_mul_f32_e32 v33, 0xbfb8aa3b, v37
	v_exp_f32_e32 v32, v32
	v_exp_f32_e32 v33, v33
	v_add_f32_e32 v32, 1.0, v32
	v_add_f32_e32 v33, 1.0, v33
	v_rcp_f32_e32 v32, v32
	v_rcp_f32_e32 v33, v33
	s_nop 0
	v_pk_mul_f32 v[32:33], v[24:25], v[32:33]
	v_mul_f32_e32 v24, 0xbfb8aa3b, v38
	v_mul_f32_e32 v25, 0xbfb8aa3b, v39
	v_exp_f32_e32 v24, v24
	v_exp_f32_e32 v25, v25
	v_add_f32_e32 v24, 1.0, v24
	v_add_f32_e32 v25, 1.0, v25
	v_rcp_f32_e32 v24, v24
	v_rcp_f32_e32 v25, v25
	s_nop 0
	v_pk_mul_f32 v[34:35], v[26:27], v[24:25]
	v_cvt_pk_bf16_f32 v24, v28, v29
	v_cvt_pk_bf16_f32 v25, v30, v31
	v_cvt_pk_bf16_f32 v26, v32, v33
	v_cvt_pk_bf16_f32 v27, v34, v35
	global_store_dwordx4 v[102:103], v[24:27], off offset:256
	s_waitcnt vmcnt(13)
	v_lshlrev_b32_e32 v28, 16, v210
	v_and_b32_e32 v29, 0xffff0000, v210
	v_lshlrev_b32_e32 v24, 16, v208
	v_and_b32_e32 v25, 0xffff0000, v208
	v_mul_f32_e32 v24, 0xbfb8aa3b, v24
	v_mul_f32_e32 v25, 0xbfb8aa3b, v25
	v_exp_f32_e32 v24, v24
	v_exp_f32_e32 v25, v25
	v_lshlrev_b32_e32 v26, 16, v209
	v_and_b32_e32 v27, 0xffff0000, v209
	v_add_f32_e32 v24, 1.0, v24
	v_add_f32_e32 v25, 1.0, v25
	v_rcp_f32_e32 v24, v24
	v_rcp_f32_e32 v25, v25
	v_lshlrev_b32_e32 v30, 16, v211
	v_and_b32_e32 v31, 0xffff0000, v211
	v_pk_mul_f32 v[20:21], v[20:21], v[24:25]
	v_mul_f32_e32 v24, 0xbfb8aa3b, v26
	v_mul_f32_e32 v25, 0xbfb8aa3b, v27
	v_exp_f32_e32 v24, v24
	v_exp_f32_e32 v25, v25
	v_add_f32_e32 v24, 1.0, v24
	v_add_f32_e32 v25, 1.0, v25
	v_rcp_f32_e32 v24, v24
	v_rcp_f32_e32 v25, v25
	s_nop 0
	v_pk_mul_f32 v[22:23], v[22:23], v[24:25]
	v_mul_f32_e32 v24, 0xbfb8aa3b, v28
	v_mul_f32_e32 v25, 0xbfb8aa3b, v29
	v_exp_f32_e32 v24, v24
	v_exp_f32_e32 v25, v25
	v_add_f32_e32 v24, 1.0, v24
	v_add_f32_e32 v25, 1.0, v25
	v_rcp_f32_e32 v24, v24
	v_rcp_f32_e32 v25, v25
	s_nop 0
	v_pk_mul_f32 v[24:25], v[16:17], v[24:25]
	v_mul_f32_e32 v16, 0xbfb8aa3b, v30
	v_mul_f32_e32 v17, 0xbfb8aa3b, v31
	v_exp_f32_e32 v16, v16
	v_exp_f32_e32 v17, v17
	v_add_f32_e32 v16, 1.0, v16
	v_add_f32_e32 v17, 1.0, v17
	v_rcp_f32_e32 v16, v16
	v_rcp_f32_e32 v17, v17
	s_nop 0
	v_pk_mul_f32 v[26:27], v[18:19], v[16:17]
	v_cvt_pk_bf16_f32 v16, v20, v21
	v_cvt_pk_bf16_f32 v17, v22, v23
	v_cvt_pk_bf16_f32 v18, v24, v25
	v_cvt_pk_bf16_f32 v19, v26, v27
	global_store_dwordx4 v[100:101], v[16:19], off offset:256
	s_waitcnt vmcnt(11)
	v_lshlrev_b32_e32 v20, 16, v206
	v_and_b32_e32 v21, 0xffff0000, v206
	v_lshlrev_b32_e32 v16, 16, v204
	v_and_b32_e32 v17, 0xffff0000, v204
	v_mul_f32_e32 v16, 0xbfb8aa3b, v16
	v_mul_f32_e32 v17, 0xbfb8aa3b, v17
	v_exp_f32_e32 v16, v16
	v_exp_f32_e32 v17, v17
	v_lshlrev_b32_e32 v18, 16, v205
	v_and_b32_e32 v19, 0xffff0000, v205
	v_add_f32_e32 v16, 1.0, v16
	v_add_f32_e32 v17, 1.0, v17
	v_rcp_f32_e32 v16, v16
	v_rcp_f32_e32 v17, v17
	v_lshlrev_b32_e32 v22, 16, v207
	v_and_b32_e32 v23, 0xffff0000, v207
	v_pk_mul_f32 v[12:13], v[12:13], v[16:17]
	v_mul_f32_e32 v16, 0xbfb8aa3b, v18
	v_mul_f32_e32 v17, 0xbfb8aa3b, v19
	v_exp_f32_e32 v16, v16
	v_exp_f32_e32 v17, v17
	v_add_f32_e32 v16, 1.0, v16
	v_add_f32_e32 v17, 1.0, v17
	v_rcp_f32_e32 v16, v16
	v_rcp_f32_e32 v17, v17
	s_nop 0
	v_pk_mul_f32 v[14:15], v[14:15], v[16:17]
	v_mul_f32_e32 v16, 0xbfb8aa3b, v20
	v_mul_f32_e32 v17, 0xbfb8aa3b, v21
	v_exp_f32_e32 v16, v16
	v_exp_f32_e32 v17, v17
	v_add_f32_e32 v16, 1.0, v16
	v_add_f32_e32 v17, 1.0, v17
	v_rcp_f32_e32 v16, v16
	v_rcp_f32_e32 v17, v17
	s_nop 0
	v_pk_mul_f32 v[16:17], v[8:9], v[16:17]
	v_mul_f32_e32 v8, 0xbfb8aa3b, v22
	v_mul_f32_e32 v9, 0xbfb8aa3b, v23
	v_exp_f32_e32 v8, v8
	v_exp_f32_e32 v9, v9
	v_add_f32_e32 v8, 1.0, v8
	v_add_f32_e32 v9, 1.0, v9
	v_rcp_f32_e32 v8, v8
	v_rcp_f32_e32 v9, v9
	s_nop 0
	v_pk_mul_f32 v[18:19], v[10:11], v[8:9]
	v_cvt_pk_bf16_f32 v8, v12, v13
	v_cvt_pk_bf16_f32 v9, v14, v15
	v_cvt_pk_bf16_f32 v10, v16, v17
	v_cvt_pk_bf16_f32 v11, v18, v19
	global_store_dwordx4 v[98:99], v[8:11], off offset:256
	s_waitcnt vmcnt(9)
	v_and_b32_e32 v14, 0xffff0000, v189
	v_lshlrev_b32_e32 v15, 16, v189
	v_and_b32_e32 v11, 0xffff0000, v188
	v_lshlrev_b32_e32 v10, 16, v188
	v_mul_f32_e32 v10, 0xbfb8aa3b, v10
	v_mul_f32_e32 v11, 0xbfb8aa3b, v11
	v_exp_f32_e32 v10, v10
	v_exp_f32_e32 v11, v11
	v_and_b32_e32 v12, 0xffff0000, v190
	v_lshlrev_b32_e32 v13, 16, v190
	v_add_f32_e32 v10, 1.0, v10
	v_add_f32_e32 v11, 1.0, v11
	v_rcp_f32_e32 v10, v10
	v_rcp_f32_e32 v11, v11
	v_and_b32_e32 v8, 0xffff0000, v191
	v_mul_f32_e32 v8, 0xbfb8aa3b, v8
	v_exp_f32_e32 v8, v8
	v_pk_mul_f32 v[4:5], v[4:5], v[10:11]
	v_mul_f32_e32 v10, 0xbfb8aa3b, v15
	v_mul_f32_e32 v11, 0xbfb8aa3b, v14
	v_exp_f32_e32 v10, v10
	v_exp_f32_e32 v11, v11
	v_add_f32_e32 v8, 1.0, v8
	v_rcp_f32_e32 v9, v8
	v_add_f32_e32 v10, 1.0, v10
	v_add_f32_e32 v11, 1.0, v11
	v_rcp_f32_e32 v10, v10
	v_rcp_f32_e32 v11, v11
	v_lshlrev_b32_e32 v8, 16, v191
	v_pk_mul_f32 v[6:7], v[6:7], v[10:11]
	v_mul_f32_e32 v10, 0xbfb8aa3b, v13
	v_mul_f32_e32 v11, 0xbfb8aa3b, v12
	v_exp_f32_e32 v10, v10
	v_exp_f32_e32 v11, v11
	v_add_f32_e32 v10, 1.0, v10
	v_add_f32_e32 v11, 1.0, v11
	v_rcp_f32_e32 v10, v10
	v_rcp_f32_e32 v11, v11
	s_nop 0
	v_pk_mul_f32 v[10:11], v[0:1], v[10:11]
	v_mul_f32_e32 v0, 0xbfb8aa3b, v8
	v_exp_f32_e32 v0, v0
	v_cvt_pk_bf16_f32 v1, v6, v7
	v_add_f32_e32 v0, 1.0, v0
	v_rcp_f32_e32 v8, v0
	v_cvt_pk_bf16_f32 v0, v4, v5
	v_pk_mul_f32 v[8:9], v[2:3], v[8:9]
	v_cvt_pk_bf16_f32 v2, v10, v11
	v_cvt_pk_bf16_f32 v3, v8, v9
	global_store_dwordx4 v[96:97], v[0:3], off offset:256
	s_cbranch_vccnz .LBB0_1038
	s_andn2_b64 vcc, exec, s[4:5]
	s_cbranch_vccnz .LBB0_1037
	s_barrier
	s_branch .LBB0_1037
